# SwiGLU fast-path epilogue reformulated: (a*b)*rcp((1+exp2(a*r*c))/r^2), two fewer packed f32 ops per output pair
# speedup vs baseline: 1.0063x; 1.0010x over previous
.Lcr0_261:
	v_mov_b32_e32 v130, v136
	v_mov_b32_e32 v145, v210
	v_readlane_b32 s0, v248, 15
	v_add_u32_e32 v130, s72, v130
	v_lshl_add_u32 v146, s91, 8, v130
	v_lshlrev_b32_e32 v148, 2, v145
	v_ashrrev_i32_e32 v149, 31, v148
	v_readlane_b32 s1, v248, 16
	v_ashrrev_i32_e32 v147, 31, v146
	v_lshlrev_b64 v[146:147], 6, v[146:147]
	v_lshl_add_u64 v[148:149], v[148:149], 2, s[0:1]
	v_lshl_add_u64 v[146:147], v[148:149], 0, v[146:147]
	s_nop 0
	s_mov_b32 s98, 0x1000
	s_mov_b32 s99, 0x0
	s_movk_i32 s0, 0x2000
	v_add_co_u32_e32 v146, vcc, s0, v146
	v_xor_b32_e32 v180, 32, v143
	s_nop 0
	v_addc_co_u32_e32 v147, vcc, 0, v147, vcc
	s_mov_b32 s98, 0x3000
	s_mov_b32 s99, 0x0
	s_nop 0
	v_and_b32_e32 v147, 64, v143
	v_xor_b32_e32 v146, 16, v143
	v_add_u32_e32 v147, 64, v147
	v_cmp_lt_i32_e32 vcc, v146, v147
	s_mul_i32 s0, s91, 44
	s_lshl_b32 s1, s10, 1
	s_nop 0
	v_cmp_lt_i32_e32 vcc, v180, v147
	s_nop 0
	s_add_i32 s0, s0, s1
	s_nop 0
	v_lshl_add_u32 v180, v145, 3, s80
	v_ashrrev_i32_e32 v146, 5, v180
	s_or_b32 s0, s0, s79
	s_ashr_i32 s1, s0, 31
	s_lshl_b64 s[0:1], s[0:1], 15
	v_lshlrev_b32_e32 v145, 4, v145
	s_add_u32 s50, s70, s0
	v_and_b32_e32 v145, 48, v145
	s_addc_u32 s51, s71, s1
	s_cmpk_lt_i32 s91, 0x80
	s_cselect_b64 s[0:1], -1, 0
	s_xor_b64 s[52:53], s[36:37], -1
	s_and_b64 s[52:53], s[52:53], s[0:1]
	s_mov_b64 s[6:7], -1
	s_and_b64 vcc, exec, s[52:53]
	s_waitcnt lgkmcnt(1)
	s_waitcnt lgkmcnt(0)
	s_waitcnt lgkmcnt(2)
	s_waitcnt lgkmcnt(4)
	s_waitcnt lgkmcnt(3)
	v_mov_b32_e32 v162, v244
	s_waitcnt lgkmcnt(3)
	s_waitcnt lgkmcnt(2)
	v_mul_f32_e32 v216, s24, v162
	v_mul_f32_e32 v218, v162, v162
	s_nop 0
	v_rcp_f32_e32 v218, v218
	v_pk_mul_f32 v[212:213], v[122:123], v[216:217] op_sel_hi:[1,0]
	v_pk_mul_f32 v[214:215], v[124:125], v[216:217] op_sel_hi:[1,0]
	v_exp_f32_e32 v212, v212
	v_exp_f32_e32 v213, v213
	v_exp_f32_e32 v214, v214
	v_exp_f32_e32 v215, v215
	v_pk_mul_f32 v[122:123], v[122:123], v[126:127]
	v_pk_fma_f32 v[212:213], v[212:213], v[218:219], v[218:219] op_sel_hi:[1,0,0]
	v_pk_mul_f32 v[124:125], v[124:125], v[128:129]
	v_pk_fma_f32 v[214:215], v[214:215], v[218:219], v[218:219] op_sel_hi:[1,0,0]
	v_rcp_f32_e32 v212, v212
	v_rcp_f32_e32 v213, v213
	v_rcp_f32_e32 v214, v214
	v_rcp_f32_e32 v215, v215
	v_pk_mul_f32 v[122:123], v[122:123], v[212:213]
	v_pk_mul_f32 v[124:125], v[124:125], v[214:215]
	v_pk_mul_f32 v[212:213], v[114:115], v[216:217] op_sel_hi:[1,0]
	v_pk_mul_f32 v[214:215], v[116:117], v[216:217] op_sel_hi:[1,0]
	v_exp_f32_e32 v212, v212
	v_exp_f32_e32 v213, v213
	v_exp_f32_e32 v214, v214
	v_exp_f32_e32 v215, v215
	v_pk_mul_f32 v[126:127], v[114:115], v[118:119]
	v_pk_fma_f32 v[212:213], v[212:213], v[218:219], v[218:219] op_sel_hi:[1,0,0]
	v_pk_mul_f32 v[128:129], v[116:117], v[120:121]
	v_pk_fma_f32 v[214:215], v[214:215], v[218:219], v[218:219] op_sel_hi:[1,0,0]
	v_rcp_f32_e32 v212, v212
	v_rcp_f32_e32 v213, v213
	v_rcp_f32_e32 v214, v214
	v_rcp_f32_e32 v215, v215
	v_pk_mul_f32 v[126:127], v[126:127], v[212:213]
	v_pk_mul_f32 v[128:129], v[128:129], v[214:215]
	s_waitcnt lgkmcnt(1)
	s_waitcnt lgkmcnt(0)
	s_nop 0
	s_nop 0
	s_nop 0
	v_lshrrev_b32_e32 v115, 3, v130
	v_lshlrev_b32_e32 v114, 7, v130
	v_and_b32_e32 v115, 14, v115
	v_and_b32_e32 v114, 0xffffc000, v114
	v_lshlrev_b32_e32 v116, 6, v130
	v_add_lshl_u32 v120, v115, v146, 10
	v_lshlrev_b32_e32 v115, 2, v130
	v_and_or_b32 v116, v116, s73, v145
	v_and_b32_e32 v115, 32, v115
	v_add_u32_e32 v114, v120, v114
	v_bitop3_b32 v114, v114, v116, v115 bitop3:0xf6
	v_ashrrev_i32_e32 v115, 31, v114
	v_lshl_add_u64 v[118:119], s[50:51], 0, v[114:115]
	v_cvt_pk_bf16_f32 v114, v122, v123
	v_cvt_pk_bf16_f32 v115, v124, v125
	v_cvt_pk_bf16_f32 v116, v126, v127
	v_cvt_pk_bf16_f32 v117, v128, v129
	v_lshl_add_u64 v[184:185], v[118:119], 0, 0
	s_cbranch_vccz .Lcr0_263
	global_store_dwordx4 v[118:119], v[114:117], off
	s_mov_b64 s[6:7], 0

.Lcr0_265:
	s_waitcnt lgkmcnt(6)
	s_nop 0
	s_nop 0
	v_mov_b32_e32 v114, v245
	s_mov_b64 s[54:55], -1
	s_andn2_b64 vcc, exec, s[52:53]
	v_mul_f32_e32 v216, s24, v114
	v_mul_f32_e32 v218, v114, v114
	s_nop 0
	v_rcp_f32_e32 v218, v218
	v_pk_mul_f32 v[212:213], v[106:107], v[216:217] op_sel_hi:[1,0]
	v_pk_mul_f32 v[214:215], v[108:109], v[216:217] op_sel_hi:[1,0]
	v_exp_f32_e32 v212, v212
	v_exp_f32_e32 v213, v213
	v_exp_f32_e32 v214, v214
	v_exp_f32_e32 v215, v215
	v_pk_mul_f32 v[106:107], v[106:107], v[110:111]
	v_pk_fma_f32 v[212:213], v[212:213], v[218:219], v[218:219] op_sel_hi:[1,0,0]
	v_pk_mul_f32 v[108:109], v[108:109], v[112:113]
	v_pk_fma_f32 v[214:215], v[214:215], v[218:219], v[218:219] op_sel_hi:[1,0,0]
	v_rcp_f32_e32 v212, v212
	v_rcp_f32_e32 v213, v213
	v_rcp_f32_e32 v214, v214
	v_rcp_f32_e32 v215, v215
	v_pk_mul_f32 v[106:107], v[106:107], v[212:213]
	v_pk_mul_f32 v[108:109], v[108:109], v[214:215]
	v_pk_mul_f32 v[212:213], v[98:99], v[216:217] op_sel_hi:[1,0]
	v_pk_mul_f32 v[214:215], v[100:101], v[216:217] op_sel_hi:[1,0]
	v_exp_f32_e32 v212, v212
	v_exp_f32_e32 v213, v213
	v_exp_f32_e32 v214, v214
	v_exp_f32_e32 v215, v215
	v_pk_mul_f32 v[110:111], v[98:99], v[102:103]
	v_pk_fma_f32 v[212:213], v[212:213], v[218:219], v[218:219] op_sel_hi:[1,0,0]
	v_pk_mul_f32 v[104:105], v[100:101], v[104:105]
	v_pk_fma_f32 v[214:215], v[214:215], v[218:219], v[218:219] op_sel_hi:[1,0,0]
	v_rcp_f32_e32 v212, v212
	v_rcp_f32_e32 v213, v213
	v_rcp_f32_e32 v214, v214
	v_rcp_f32_e32 v215, v215
	v_pk_mul_f32 v[110:111], v[110:111], v[212:213]
	v_pk_mul_f32 v[104:105], v[104:105], v[214:215]
	s_nop 0
	s_nop 0
	s_nop 0
	s_nop 0
	s_nop 0
	v_cvt_pk_bf16_f32 v101, v104, v105
	v_cndmask_b32_e64 v104, 0, 1, s[52:53]
	v_cvt_pk_bf16_f32 v98, v106, v107
	v_cvt_pk_bf16_f32 v99, v108, v109
	v_cvt_pk_bf16_f32 v100, v110, v111
	v_cmp_ne_u32_e64 s[6:7], 1, v104
	s_cbranch_vccnz .Lcr0_267
	s_mov_b64 s[54:55], 0
	global_store_dwordx4 v[186:187], v[98:101], off offset:-2048

.Lcr0_269:
	s_waitcnt lgkmcnt(5)
	s_nop 0
	s_nop 0
	v_mov_b32_e32 v98, v246
	s_mov_b64 s[52:53], -1
	s_and_b64 vcc, exec, s[6:7]
	v_mul_f32_e32 v216, s24, v98
	v_mul_f32_e32 v218, v98, v98
	s_nop 0
	v_rcp_f32_e32 v218, v218
	v_pk_mul_f32 v[212:213], v[90:91], v[216:217] op_sel_hi:[1,0]
	v_pk_mul_f32 v[214:215], v[92:93], v[216:217] op_sel_hi:[1,0]
	v_exp_f32_e32 v212, v212
	v_exp_f32_e32 v213, v213
	v_exp_f32_e32 v214, v214
	v_exp_f32_e32 v215, v215
	v_pk_mul_f32 v[90:91], v[90:91], v[94:95]
	v_pk_fma_f32 v[212:213], v[212:213], v[218:219], v[218:219] op_sel_hi:[1,0,0]
	v_pk_mul_f32 v[92:93], v[92:93], v[96:97]
	v_pk_fma_f32 v[214:215], v[214:215], v[218:219], v[218:219] op_sel_hi:[1,0,0]
	v_rcp_f32_e32 v212, v212
	v_rcp_f32_e32 v213, v213
	v_rcp_f32_e32 v214, v214
	v_rcp_f32_e32 v215, v215
	v_pk_mul_f32 v[90:91], v[90:91], v[212:213]
	v_pk_mul_f32 v[92:93], v[92:93], v[214:215]
	v_pk_mul_f32 v[212:213], v[82:83], v[216:217] op_sel_hi:[1,0]
	v_pk_mul_f32 v[214:215], v[84:85], v[216:217] op_sel_hi:[1,0]
	v_exp_f32_e32 v212, v212
	v_exp_f32_e32 v213, v213
	v_exp_f32_e32 v214, v214
	v_exp_f32_e32 v215, v215
	v_pk_mul_f32 v[94:95], v[82:83], v[86:87]
	v_pk_fma_f32 v[212:213], v[212:213], v[218:219], v[218:219] op_sel_hi:[1,0,0]
	v_pk_mul_f32 v[88:89], v[84:85], v[88:89]
	v_pk_fma_f32 v[214:215], v[214:215], v[218:219], v[218:219] op_sel_hi:[1,0,0]
	v_rcp_f32_e32 v212, v212
	v_rcp_f32_e32 v213, v213
	v_rcp_f32_e32 v214, v214
	v_rcp_f32_e32 v215, v215
	v_pk_mul_f32 v[94:95], v[94:95], v[212:213]
	v_pk_mul_f32 v[88:89], v[88:89], v[214:215]
	s_nop 0
	v_cvt_pk_bf16_f32 v82, v90, v91
	v_cvt_pk_bf16_f32 v83, v92, v93
	v_cvt_pk_bf16_f32 v84, v94, v95
	v_cvt_pk_bf16_f32 v85, v88, v89
	s_cbranch_vccnz .Lcr0_271
	s_mov_b64 s[52:53], 0
	global_store_dwordx4 v[186:187], v[82:85], off

.Lcr0_273:
	s_waitcnt lgkmcnt(4)
	s_nop 0
	s_nop 0
	v_mov_b32_e32 v82, v247
	s_mov_b64 s[52:53], -1
	s_and_b64 vcc, exec, s[6:7]
	v_mul_f32_e32 v216, s24, v82
	v_mul_f32_e32 v218, v82, v82
	s_nop 0
	v_rcp_f32_e32 v218, v218
	v_pk_mul_f32 v[212:213], v[74:75], v[216:217] op_sel_hi:[1,0]
	v_pk_mul_f32 v[214:215], v[76:77], v[216:217] op_sel_hi:[1,0]
	v_exp_f32_e32 v212, v212
	v_exp_f32_e32 v213, v213
	v_exp_f32_e32 v214, v214
	v_exp_f32_e32 v215, v215
	v_pk_mul_f32 v[74:75], v[74:75], v[78:79]
	v_pk_fma_f32 v[212:213], v[212:213], v[218:219], v[218:219] op_sel_hi:[1,0,0]
	v_pk_mul_f32 v[76:77], v[76:77], v[80:81]
	v_pk_fma_f32 v[214:215], v[214:215], v[218:219], v[218:219] op_sel_hi:[1,0,0]
	v_rcp_f32_e32 v212, v212
	v_rcp_f32_e32 v213, v213
	v_rcp_f32_e32 v214, v214
	v_rcp_f32_e32 v215, v215
	v_pk_mul_f32 v[74:75], v[74:75], v[212:213]
	v_pk_mul_f32 v[76:77], v[76:77], v[214:215]
	v_pk_mul_f32 v[212:213], v[66:67], v[216:217] op_sel_hi:[1,0]
	v_pk_mul_f32 v[214:215], v[68:69], v[216:217] op_sel_hi:[1,0]
	v_exp_f32_e32 v212, v212
	v_exp_f32_e32 v213, v213
	v_exp_f32_e32 v214, v214
	v_exp_f32_e32 v215, v215
	v_pk_mul_f32 v[78:79], v[66:67], v[70:71]
	v_pk_fma_f32 v[212:213], v[212:213], v[218:219], v[218:219] op_sel_hi:[1,0,0]
	v_pk_mul_f32 v[72:73], v[68:69], v[72:73]
	v_pk_fma_f32 v[214:215], v[214:215], v[218:219], v[218:219] op_sel_hi:[1,0,0]
	v_rcp_f32_e32 v212, v212
	v_rcp_f32_e32 v213, v213
	v_rcp_f32_e32 v214, v214
	v_rcp_f32_e32 v215, v215
	v_pk_mul_f32 v[78:79], v[78:79], v[212:213]
	v_pk_mul_f32 v[72:73], v[72:73], v[214:215]
	s_nop 0
	v_cvt_pk_bf16_f32 v66, v74, v75
	v_cvt_pk_bf16_f32 v67, v76, v77
	v_cvt_pk_bf16_f32 v68, v78, v79
	v_cvt_pk_bf16_f32 v69, v72, v73
	s_cbranch_vccnz .Lcr0_275
	s_mov_b64 s[52:53], 0
	global_store_dwordx4 v[186:187], v[66:69], off offset:2048

.Lcr0_277:
	s_waitcnt lgkmcnt(3)
	s_nop 0
	s_nop 0
	v_mov_b32_e32 v66, v250
	s_nop 0
	s_mov_b64 s[52:53], -1
	v_mul_f32_e32 v216, s24, v66
	v_mul_f32_e32 v218, v66, v66
	s_nop 0
	v_rcp_f32_e32 v218, v218
	v_pk_mul_f32 v[212:213], v[58:59], v[216:217] op_sel_hi:[1,0]
	v_pk_mul_f32 v[214:215], v[60:61], v[216:217] op_sel_hi:[1,0]
	v_exp_f32_e32 v212, v212
	v_exp_f32_e32 v213, v213
	v_exp_f32_e32 v214, v214
	v_exp_f32_e32 v215, v215
	v_pk_mul_f32 v[58:59], v[58:59], v[62:63]
	v_pk_fma_f32 v[212:213], v[212:213], v[218:219], v[218:219] op_sel_hi:[1,0,0]
	v_pk_mul_f32 v[60:61], v[60:61], v[64:65]
	v_pk_fma_f32 v[214:215], v[214:215], v[218:219], v[218:219] op_sel_hi:[1,0,0]
	v_rcp_f32_e32 v212, v212
	v_rcp_f32_e32 v213, v213
	v_rcp_f32_e32 v214, v214
	v_rcp_f32_e32 v215, v215
	v_pk_mul_f32 v[58:59], v[58:59], v[212:213]
	v_pk_mul_f32 v[60:61], v[60:61], v[214:215]
	v_pk_mul_f32 v[212:213], v[50:51], v[216:217] op_sel_hi:[1,0]
	v_pk_mul_f32 v[214:215], v[52:53], v[216:217] op_sel_hi:[1,0]
	v_exp_f32_e32 v212, v212
	v_exp_f32_e32 v213, v213
	v_exp_f32_e32 v214, v214
	v_exp_f32_e32 v215, v215
	v_pk_mul_f32 v[62:63], v[50:51], v[54:55]
	v_pk_fma_f32 v[212:213], v[212:213], v[218:219], v[218:219] op_sel_hi:[1,0,0]
	v_pk_mul_f32 v[56:57], v[52:53], v[56:57]
	v_pk_fma_f32 v[214:215], v[214:215], v[218:219], v[218:219] op_sel_hi:[1,0,0]
	v_rcp_f32_e32 v212, v212
	v_rcp_f32_e32 v213, v213
	v_rcp_f32_e32 v214, v214
	v_rcp_f32_e32 v215, v215
	v_pk_mul_f32 v[62:63], v[62:63], v[212:213]
	v_pk_mul_f32 v[56:57], v[56:57], v[214:215]
	s_and_b64 vcc, exec, s[6:7]
	s_nop 0
	v_cvt_pk_bf16_f32 v50, v58, v59
	v_cvt_pk_bf16_f32 v51, v60, v61
	v_cvt_pk_bf16_f32 v52, v62, v63
	v_cvt_pk_bf16_f32 v53, v56, v57
	s_mov_b32 s98, 0x5000
	s_mov_b32 s99, 0x0
	v_lshl_add_u64 v[186:187], v[184:185], 0, s[98:99]
	s_cbranch_vccnz .Lcr0_279
	s_mov_b64 s[52:53], 0
	global_store_dwordx4 v[186:187], v[50:53], off offset:-4096

.Lcr0_281:
	s_waitcnt lgkmcnt(2)
	s_nop 0
	s_nop 0
	v_mov_b32_e32 v50, v251
	s_mov_b64 s[52:53], -1
	s_and_b64 vcc, exec, s[6:7]
	v_mul_f32_e32 v216, s24, v50
	v_mul_f32_e32 v218, v50, v50
	s_nop 0
	v_rcp_f32_e32 v218, v218
	v_pk_mul_f32 v[212:213], v[42:43], v[216:217] op_sel_hi:[1,0]
	v_pk_mul_f32 v[214:215], v[44:45], v[216:217] op_sel_hi:[1,0]
	v_exp_f32_e32 v212, v212
	v_exp_f32_e32 v213, v213
	v_exp_f32_e32 v214, v214
	v_exp_f32_e32 v215, v215
	v_pk_mul_f32 v[42:43], v[42:43], v[46:47]
	v_pk_fma_f32 v[212:213], v[212:213], v[218:219], v[218:219] op_sel_hi:[1,0,0]
	v_pk_mul_f32 v[44:45], v[44:45], v[48:49]
	v_pk_fma_f32 v[214:215], v[214:215], v[218:219], v[218:219] op_sel_hi:[1,0,0]
	v_rcp_f32_e32 v212, v212
	v_rcp_f32_e32 v213, v213
	v_rcp_f32_e32 v214, v214
	v_rcp_f32_e32 v215, v215
	v_pk_mul_f32 v[42:43], v[42:43], v[212:213]
	v_pk_mul_f32 v[44:45], v[44:45], v[214:215]
	v_pk_mul_f32 v[212:213], v[34:35], v[216:217] op_sel_hi:[1,0]
	v_pk_mul_f32 v[214:215], v[36:37], v[216:217] op_sel_hi:[1,0]
	v_exp_f32_e32 v212, v212
	v_exp_f32_e32 v213, v213
	v_exp_f32_e32 v214, v214
	v_exp_f32_e32 v215, v215
	v_pk_mul_f32 v[46:47], v[34:35], v[38:39]
	v_pk_fma_f32 v[212:213], v[212:213], v[218:219], v[218:219] op_sel_hi:[1,0,0]
	v_pk_mul_f32 v[40:41], v[36:37], v[40:41]
	v_pk_fma_f32 v[214:215], v[214:215], v[218:219], v[218:219] op_sel_hi:[1,0,0]
	v_rcp_f32_e32 v212, v212
	v_rcp_f32_e32 v213, v213
	v_rcp_f32_e32 v214, v214
	v_rcp_f32_e32 v215, v215
	v_pk_mul_f32 v[46:47], v[46:47], v[212:213]
	v_pk_mul_f32 v[40:41], v[40:41], v[214:215]
	s_nop 0
	v_cvt_pk_bf16_f32 v34, v42, v43
	v_cvt_pk_bf16_f32 v35, v44, v45
	v_cvt_pk_bf16_f32 v36, v46, v47
	v_cvt_pk_bf16_f32 v37, v40, v41
	s_cbranch_vccnz .Lcr0_283
	s_mov_b64 s[52:53], 0
	global_store_dwordx4 v[186:187], v[34:37], off offset:-2048

.Lcr0_285:
	s_waitcnt lgkmcnt(1)
	s_nop 0
	s_nop 0
	v_mov_b32_e32 v34, v252
	s_mov_b64 s[52:53], -1
	s_and_b64 vcc, exec, s[6:7]
	v_mul_f32_e32 v216, s24, v34
	v_mul_f32_e32 v218, v34, v34
	s_nop 0
	v_rcp_f32_e32 v218, v218
	v_pk_mul_f32 v[212:213], v[26:27], v[216:217] op_sel_hi:[1,0]
	v_pk_mul_f32 v[214:215], v[28:29], v[216:217] op_sel_hi:[1,0]
	v_exp_f32_e32 v212, v212
	v_exp_f32_e32 v213, v213
	v_exp_f32_e32 v214, v214
	v_exp_f32_e32 v215, v215
	v_pk_mul_f32 v[26:27], v[26:27], v[30:31]
	v_pk_fma_f32 v[212:213], v[212:213], v[218:219], v[218:219] op_sel_hi:[1,0,0]
	v_pk_mul_f32 v[28:29], v[28:29], v[32:33]
	v_pk_fma_f32 v[214:215], v[214:215], v[218:219], v[218:219] op_sel_hi:[1,0,0]
	v_rcp_f32_e32 v212, v212
	v_rcp_f32_e32 v213, v213
	v_rcp_f32_e32 v214, v214
	v_rcp_f32_e32 v215, v215
	v_pk_mul_f32 v[26:27], v[26:27], v[212:213]
	v_pk_mul_f32 v[28:29], v[28:29], v[214:215]
	v_pk_mul_f32 v[212:213], v[18:19], v[216:217] op_sel_hi:[1,0]
	v_pk_mul_f32 v[214:215], v[20:21], v[216:217] op_sel_hi:[1,0]
	v_exp_f32_e32 v212, v212
	v_exp_f32_e32 v213, v213
	v_exp_f32_e32 v214, v214
	v_exp_f32_e32 v215, v215
	v_pk_mul_f32 v[30:31], v[18:19], v[22:23]
	v_pk_fma_f32 v[212:213], v[212:213], v[218:219], v[218:219] op_sel_hi:[1,0,0]
	v_pk_mul_f32 v[24:25], v[20:21], v[24:25]
	v_pk_fma_f32 v[214:215], v[214:215], v[218:219], v[218:219] op_sel_hi:[1,0,0]
	v_rcp_f32_e32 v212, v212
	v_rcp_f32_e32 v213, v213
	v_rcp_f32_e32 v214, v214
	v_rcp_f32_e32 v215, v215
	v_pk_mul_f32 v[30:31], v[30:31], v[212:213]
	v_pk_mul_f32 v[24:25], v[24:25], v[214:215]
	s_nop 0
	v_cvt_pk_bf16_f32 v18, v26, v27
	v_cvt_pk_bf16_f32 v19, v28, v29
	v_cvt_pk_bf16_f32 v20, v30, v31
	v_cvt_pk_bf16_f32 v21, v24, v25
	s_cbranch_vccnz .Lcr0_287
	s_mov_b64 s[52:53], 0
	global_store_dwordx4 v[186:187], v[18:21], off

.Lcr0_289:
	s_waitcnt lgkmcnt(0)
	s_nop 0
	s_nop 0
	v_mov_b32_e32 v18, v253
	s_and_b64 vcc, exec, s[6:7]
	v_mul_f32_e32 v216, s24, v18
	v_mul_f32_e32 v218, v18, v18
	s_nop 0
	v_rcp_f32_e32 v218, v218
	v_pk_mul_f32 v[212:213], v[10:11], v[216:217] op_sel_hi:[1,0]
	v_pk_mul_f32 v[214:215], v[12:13], v[216:217] op_sel_hi:[1,0]
	v_exp_f32_e32 v212, v212
	v_exp_f32_e32 v213, v213
	v_exp_f32_e32 v214, v214
	v_exp_f32_e32 v215, v215
	v_pk_mul_f32 v[10:11], v[10:11], v[14:15]
	v_pk_fma_f32 v[212:213], v[212:213], v[218:219], v[218:219] op_sel_hi:[1,0,0]
	v_pk_mul_f32 v[12:13], v[12:13], v[16:17]
	v_pk_fma_f32 v[214:215], v[214:215], v[218:219], v[218:219] op_sel_hi:[1,0,0]
	v_rcp_f32_e32 v212, v212
	v_rcp_f32_e32 v213, v213
	v_rcp_f32_e32 v214, v214
	v_rcp_f32_e32 v215, v215
	v_pk_mul_f32 v[10:11], v[10:11], v[212:213]
	v_pk_mul_f32 v[12:13], v[12:13], v[214:215]
	v_pk_mul_f32 v[212:213], v[2:3], v[216:217] op_sel_hi:[1,0]
	v_pk_mul_f32 v[214:215], v[4:5], v[216:217] op_sel_hi:[1,0]
	v_exp_f32_e32 v212, v212
	v_exp_f32_e32 v213, v213
	v_exp_f32_e32 v214, v214
	v_exp_f32_e32 v215, v215
	v_pk_mul_f32 v[14:15], v[2:3], v[6:7]
	v_pk_fma_f32 v[212:213], v[212:213], v[218:219], v[218:219] op_sel_hi:[1,0,0]
	v_pk_mul_f32 v[8:9], v[4:5], v[8:9]
	v_pk_fma_f32 v[214:215], v[214:215], v[218:219], v[218:219] op_sel_hi:[1,0,0]
	v_rcp_f32_e32 v212, v212
	v_rcp_f32_e32 v213, v213
	v_rcp_f32_e32 v214, v214
	v_rcp_f32_e32 v215, v215
	v_pk_mul_f32 v[14:15], v[14:15], v[212:213]
	v_pk_mul_f32 v[8:9], v[8:9], v[214:215]
	s_nop 0
	v_cvt_pk_bf16_f32 v2, v10, v11
	v_cvt_pk_bf16_f32 v3, v12, v13
	v_cvt_pk_bf16_f32 v4, v14, v15
	v_cvt_pk_bf16_f32 v5, v8, v9
	s_mov_b64 s[50:51], -1
	s_cbranch_vccnz .Lcr0_291
	s_mov_b64 s[50:51], 0
	global_store_dwordx4 v[186:187], v[2:5], off offset:2048

.Lcr1_2126:
	v_mov_b32_e32 v137, v210
	v_mov_b32_e32 v130, v202
	v_xor_b32_e32 v138, 32, v204
	v_add_u32_e32 v136, s68, v130
	v_lshl_add_u32 v130, s82, 8, v136
	v_lshlrev_b32_e32 v132, 2, v137
	v_ashrrev_i32_e32 v133, 31, v132
	v_ashrrev_i32_e32 v131, 31, v130
	v_lshl_add_u64 v[132:133], v[132:133], 2, s[2:3]
	v_lshlrev_b64 v[130:131], 6, v[130:131]
	v_lshl_add_u64 v[134:135], v[132:133], 0, v[130:131]
	s_mov_b32 s98, 0x1000
	s_mov_b32 s99, 0x0
	v_add_co_u32_e32 v134, vcc, s13, v134
	s_mul_i32 s10, s82, 44
	s_nop 0
	v_addc_co_u32_e32 v135, vcc, 0, v135, vcc
	v_and_b32_e32 v135, 64, v204
	v_xor_b32_e32 v134, 16, v204
	v_add_u32_e32 v135, 64, v135
	v_cmp_lt_i32_e32 vcc, v134, v135
	s_lshl_b32 s11, s12, 1
	s_add_i32 s10, s10, s11
	v_cndmask_b32_e32 v134, v204, v134, vcc
	v_cmp_lt_i32_e32 vcc, v138, v135
	v_lshlrev_b32_e32 v139, 2, v134
	s_or_b32 s10, s10, s74
	s_nop 0
	s_nop 0
	s_ashr_i32 s11, s10, 31
	v_lshl_add_u32 v138, v137, 3, s75
	s_lshl_b64 s[10:11], s[10:11], 15
	v_lshlrev_b32_e32 v137, 4, v137
	v_ashrrev_i32_e32 v138, 5, v138
	s_add_u32 s50, s65, s10
	v_and_b32_e32 v137, 48, v137
	s_addc_u32 s51, s66, s11
	s_cmpk_lt_i32 s82, 0x80
	s_cselect_b64 s[52:53], -1, 0
	s_xor_b64 s[54:55], s[36:37], -1
	s_and_b64 s[52:53], s[54:55], s[52:53]
	s_mov_b64 s[10:11], -1
	s_and_b64 vcc, exec, s[52:53]
	v_add_f32_e32 v135, v152, v153
	v_add_f32_e32 v140, v154, v155
	v_add_f32_e32 v135, v135, v140
	ds_bpermute_b32 v144, v139, v135
	s_waitcnt lgkmcnt(4)
	s_waitcnt lgkmcnt(3)
	s_waitcnt lgkmcnt(1)
	v_mov_b32_e32 v130, v244
	v_add_f32_e32 v145, v135, v144
	v_mul_f32_e32 v216, s30, v130
	v_mul_f32_e32 v218, v130, v130
	s_nop 0
	v_rcp_f32_e32 v218, v218
	v_pk_mul_f32 v[212:213], v[128:129], v[216:217] op_sel_hi:[1,0]
	v_pk_mul_f32 v[214:215], v[126:127], v[216:217] op_sel_hi:[1,0]
	v_exp_f32_e32 v212, v212
	v_exp_f32_e32 v213, v213
	v_exp_f32_e32 v214, v214
	v_exp_f32_e32 v215, v215
	v_pk_mul_f32 v[154:155], v[128:129], v[96:97]
	v_pk_fma_f32 v[212:213], v[212:213], v[218:219], v[218:219] op_sel_hi:[1,0,0]
	v_pk_mul_f32 v[132:133], v[126:127], v[94:95]
	v_pk_fma_f32 v[214:215], v[214:215], v[218:219], v[218:219] op_sel_hi:[1,0,0]
	v_rcp_f32_e32 v212, v212
	v_rcp_f32_e32 v213, v213
	v_rcp_f32_e32 v214, v214
	v_rcp_f32_e32 v215, v215
	v_pk_mul_f32 v[154:155], v[154:155], v[212:213]
	v_pk_mul_f32 v[132:133], v[132:133], v[214:215]
	v_pk_mul_f32 v[212:213], v[122:123], v[216:217] op_sel_hi:[1,0]
	v_pk_mul_f32 v[214:215], v[124:125], v[216:217] op_sel_hi:[1,0]
	v_exp_f32_e32 v212, v212
	v_exp_f32_e32 v213, v213
	v_exp_f32_e32 v214, v214
	v_exp_f32_e32 v215, v215
	v_pk_mul_f32 v[160:161], v[122:123], v[90:91]
	v_pk_fma_f32 v[212:213], v[212:213], v[218:219], v[218:219] op_sel_hi:[1,0,0]
	v_pk_mul_f32 v[156:157], v[124:125], v[92:93]
	v_pk_fma_f32 v[214:215], v[214:215], v[218:219], v[218:219] op_sel_hi:[1,0,0]
	v_rcp_f32_e32 v212, v212
	v_rcp_f32_e32 v213, v213
	v_rcp_f32_e32 v214, v214
	v_rcp_f32_e32 v215, v215
	v_pk_mul_f32 v[160:161], v[160:161], v[212:213]
	v_pk_mul_f32 v[156:157], v[156:157], v[214:215]
	s_waitcnt lgkmcnt(0)
	s_nop 0
	s_nop 0
	s_waitcnt lgkmcnt(1)
	v_lshrrev_b32_e32 v131, 3, v136
	s_waitcnt lgkmcnt(0)
	v_lshlrev_b32_e32 v130, 7, v136
	v_and_b32_e32 v131, 14, v131
	v_and_b32_e32 v130, 0xffffc000, v130
	v_lshlrev_b32_e32 v134, 6, v136
	v_add_lshl_u32 v147, v131, v138, 10
	v_lshlrev_b32_e32 v131, 2, v136
	v_and_or_b32 v134, v134, s69, v137
	v_and_b32_e32 v131, 32, v131
	v_add_u32_e32 v130, v147, v130
	v_bitop3_b32 v130, v130, v134, v131 bitop3:0xf6
	v_ashrrev_i32_e32 v131, 31, v130
	v_lshl_add_u64 v[134:135], s[50:51], 0, v[130:131]
	v_cvt_pk_bf16_f32 v130, v132, v133
	v_cvt_pk_bf16_f32 v131, v154, v155
	v_cvt_pk_bf16_f32 v132, v160, v161
	v_cvt_pk_bf16_f32 v133, v156, v157
	v_lshl_add_u64 v[170:171], v[134:135], 0, 0
	s_cbranch_vccz .Lcr1_2128
	global_store_dwordx4 v[134:135], v[130:133], off
	s_mov_b64 s[10:11], 0

.Lcr1_2130:
	s_waitcnt lgkmcnt(6)
	s_nop 0
	s_nop 0
	v_mov_b32_e32 v130, v245
	s_andn2_b64 vcc, exec, s[52:53]
	v_mul_f32_e32 v216, s30, v130
	v_mul_f32_e32 v218, v130, v130
	s_nop 0
	v_rcp_f32_e32 v218, v218
	v_pk_mul_f32 v[212:213], v[118:119], v[216:217] op_sel_hi:[1,0]
	v_pk_mul_f32 v[214:215], v[120:121], v[216:217] op_sel_hi:[1,0]
	v_exp_f32_e32 v212, v212
	v_exp_f32_e32 v213, v213
	v_exp_f32_e32 v214, v214
	v_exp_f32_e32 v215, v215
	v_pk_mul_f32 v[132:133], v[118:119], v[86:87]
	v_pk_fma_f32 v[212:213], v[212:213], v[218:219], v[218:219] op_sel_hi:[1,0,0]
	v_pk_mul_f32 v[152:153], v[120:121], v[88:89]
	v_pk_fma_f32 v[214:215], v[214:215], v[218:219], v[218:219] op_sel_hi:[1,0,0]
	v_rcp_f32_e32 v212, v212
	v_rcp_f32_e32 v213, v213
	v_rcp_f32_e32 v214, v214
	v_rcp_f32_e32 v215, v215
	v_pk_mul_f32 v[132:133], v[132:133], v[212:213]
	v_pk_mul_f32 v[152:153], v[152:153], v[214:215]
	v_pk_mul_f32 v[212:213], v[114:115], v[216:217] op_sel_hi:[1,0]
	v_pk_mul_f32 v[214:215], v[116:117], v[216:217] op_sel_hi:[1,0]
	v_exp_f32_e32 v212, v212
	v_exp_f32_e32 v213, v213
	v_exp_f32_e32 v214, v214
	v_exp_f32_e32 v215, v215
	v_pk_mul_f32 v[154:155], v[114:115], v[82:83]
	v_pk_fma_f32 v[212:213], v[212:213], v[218:219], v[218:219] op_sel_hi:[1,0,0]
	v_pk_mul_f32 v[156:157], v[116:117], v[84:85]
	v_pk_fma_f32 v[214:215], v[214:215], v[218:219], v[218:219] op_sel_hi:[1,0,0]
	v_rcp_f32_e32 v212, v212
	v_rcp_f32_e32 v213, v213
	v_rcp_f32_e32 v214, v214
	v_rcp_f32_e32 v215, v215
	v_pk_mul_f32 v[154:155], v[154:155], v[212:213]
	v_pk_mul_f32 v[156:157], v[156:157], v[214:215]
	s_nop 0
	s_nop 0
	s_nop 0
	s_nop 0
	v_cvt_pk_bf16_f32 v131, v152, v153
	v_cndmask_b32_e64 v152, 0, 1, s[52:53]
	v_cvt_pk_bf16_f32 v130, v132, v133
	v_cvt_pk_bf16_f32 v132, v154, v155
	v_cvt_pk_bf16_f32 v133, v156, v157
	v_cmp_ne_u32_e64 s[10:11], 1, v152
	s_mov_b64 s[52:53], -1
	s_cbranch_vccnz .Lcr1_2132
	s_mov_b64 s[52:53], 0
	global_store_dwordx4 v[172:173], v[130:133], off offset:-2048

.Lcr1_2134:
	s_waitcnt lgkmcnt(5)
	s_nop 0
	s_nop 0
	v_mov_b32_e32 v130, v246
	s_and_b64 vcc, exec, s[10:11]
	s_mov_b64 s[52:53], -1
	v_mul_f32_e32 v216, s30, v130
	v_mul_f32_e32 v218, v130, v130
	s_nop 0
	v_rcp_f32_e32 v218, v218
	v_pk_mul_f32 v[212:213], v[110:111], v[216:217] op_sel_hi:[1,0]
	v_pk_mul_f32 v[214:215], v[112:113], v[216:217] op_sel_hi:[1,0]
	v_exp_f32_e32 v212, v212
	v_exp_f32_e32 v213, v213
	v_exp_f32_e32 v214, v214
	v_exp_f32_e32 v215, v215
	v_pk_mul_f32 v[132:133], v[110:111], v[78:79]
	v_pk_fma_f32 v[212:213], v[212:213], v[218:219], v[218:219] op_sel_hi:[1,0,0]
	v_pk_mul_f32 v[150:151], v[112:113], v[80:81]
	v_pk_fma_f32 v[214:215], v[214:215], v[218:219], v[218:219] op_sel_hi:[1,0,0]
	v_rcp_f32_e32 v212, v212
	v_rcp_f32_e32 v213, v213
	v_rcp_f32_e32 v214, v214
	v_rcp_f32_e32 v215, v215
	v_pk_mul_f32 v[132:133], v[132:133], v[212:213]
	v_pk_mul_f32 v[150:151], v[150:151], v[214:215]
	v_pk_mul_f32 v[212:213], v[106:107], v[216:217] op_sel_hi:[1,0]
	v_pk_mul_f32 v[214:215], v[108:109], v[216:217] op_sel_hi:[1,0]
	v_exp_f32_e32 v212, v212
	v_exp_f32_e32 v213, v213
	v_exp_f32_e32 v214, v214
	v_exp_f32_e32 v215, v215
	v_pk_mul_f32 v[152:153], v[106:107], v[74:75]
	v_pk_fma_f32 v[212:213], v[212:213], v[218:219], v[218:219] op_sel_hi:[1,0,0]
	v_pk_mul_f32 v[154:155], v[108:109], v[76:77]
	v_pk_fma_f32 v[214:215], v[214:215], v[218:219], v[218:219] op_sel_hi:[1,0,0]
	v_rcp_f32_e32 v212, v212
	v_rcp_f32_e32 v213, v213
	v_rcp_f32_e32 v214, v214
	v_rcp_f32_e32 v215, v215
	v_pk_mul_f32 v[152:153], v[152:153], v[212:213]
	v_pk_mul_f32 v[154:155], v[154:155], v[214:215]
	v_cvt_pk_bf16_f32 v130, v132, v133
	v_cvt_pk_bf16_f32 v131, v150, v151
	v_cvt_pk_bf16_f32 v132, v152, v153
	v_cvt_pk_bf16_f32 v133, v154, v155
	s_cbranch_vccnz .Lcr1_2136
	s_mov_b64 s[52:53], 0
	global_store_dwordx4 v[172:173], v[130:133], off

.Lcr1_2138:
	s_waitcnt lgkmcnt(4)
	s_nop 0
	s_nop 0
	v_mov_b32_e32 v130, v247
	s_and_b64 vcc, exec, s[10:11]
	s_mov_b64 s[52:53], -1
	v_mul_f32_e32 v216, s30, v130
	v_mul_f32_e32 v218, v130, v130
	s_nop 0
	v_rcp_f32_e32 v218, v218
	v_pk_mul_f32 v[212:213], v[102:103], v[216:217] op_sel_hi:[1,0]
	v_pk_mul_f32 v[214:215], v[104:105], v[216:217] op_sel_hi:[1,0]
	v_exp_f32_e32 v212, v212
	v_exp_f32_e32 v213, v213
	v_exp_f32_e32 v214, v214
	v_exp_f32_e32 v215, v215
	v_pk_mul_f32 v[132:133], v[102:103], v[70:71]
	v_pk_fma_f32 v[212:213], v[212:213], v[218:219], v[218:219] op_sel_hi:[1,0,0]
	v_pk_mul_f32 v[148:149], v[104:105], v[72:73]
	v_pk_fma_f32 v[214:215], v[214:215], v[218:219], v[218:219] op_sel_hi:[1,0,0]
	v_rcp_f32_e32 v212, v212
	v_rcp_f32_e32 v213, v213
	v_rcp_f32_e32 v214, v214
	v_rcp_f32_e32 v215, v215
	v_pk_mul_f32 v[132:133], v[132:133], v[212:213]
	v_pk_mul_f32 v[148:149], v[148:149], v[214:215]
	v_pk_mul_f32 v[212:213], v[98:99], v[216:217] op_sel_hi:[1,0]
	v_pk_mul_f32 v[214:215], v[100:101], v[216:217] op_sel_hi:[1,0]
	v_exp_f32_e32 v212, v212
	v_exp_f32_e32 v213, v213
	v_exp_f32_e32 v214, v214
	v_exp_f32_e32 v215, v215
	v_pk_mul_f32 v[150:151], v[98:99], v[66:67]
	v_pk_fma_f32 v[212:213], v[212:213], v[218:219], v[218:219] op_sel_hi:[1,0,0]
	v_pk_mul_f32 v[152:153], v[100:101], v[68:69]
	v_pk_fma_f32 v[214:215], v[214:215], v[218:219], v[218:219] op_sel_hi:[1,0,0]
	v_rcp_f32_e32 v212, v212
	v_rcp_f32_e32 v213, v213
	v_rcp_f32_e32 v214, v214
	v_rcp_f32_e32 v215, v215
	v_pk_mul_f32 v[150:151], v[150:151], v[212:213]
	v_pk_mul_f32 v[152:153], v[152:153], v[214:215]
	v_cvt_pk_bf16_f32 v130, v132, v133
	v_cvt_pk_bf16_f32 v131, v148, v149
	v_cvt_pk_bf16_f32 v132, v150, v151
	v_cvt_pk_bf16_f32 v133, v152, v153
	s_cbranch_vccnz .Lcr1_2140
	s_mov_b64 s[52:53], 0
	global_store_dwordx4 v[172:173], v[130:133], off offset:2048

.Lcr1_2142:
	s_waitcnt lgkmcnt(3)
	s_nop 0
	s_nop 0
	v_mov_b32_e32 v130, v250
	s_nop 0
	s_and_b64 vcc, exec, s[10:11]
	v_mul_f32_e32 v216, s30, v130
	v_mul_f32_e32 v218, v130, v130
	s_nop 0
	v_rcp_f32_e32 v218, v218
	v_pk_mul_f32 v[212:213], v[62:63], v[216:217] op_sel_hi:[1,0]
	v_pk_mul_f32 v[214:215], v[64:65], v[216:217] op_sel_hi:[1,0]
	v_exp_f32_e32 v212, v212
	v_exp_f32_e32 v213, v213
	v_exp_f32_e32 v214, v214
	v_exp_f32_e32 v215, v215
	v_pk_mul_f32 v[132:133], v[62:63], v[30:31]
	v_pk_fma_f32 v[212:213], v[212:213], v[218:219], v[218:219] op_sel_hi:[1,0,0]
	v_pk_mul_f32 v[148:149], v[64:65], v[32:33]
	v_pk_fma_f32 v[214:215], v[214:215], v[218:219], v[218:219] op_sel_hi:[1,0,0]
	v_rcp_f32_e32 v212, v212
	v_rcp_f32_e32 v213, v213
	v_rcp_f32_e32 v214, v214
	v_rcp_f32_e32 v215, v215
	v_pk_mul_f32 v[132:133], v[132:133], v[212:213]
	v_pk_mul_f32 v[148:149], v[148:149], v[214:215]
	v_pk_mul_f32 v[212:213], v[58:59], v[216:217] op_sel_hi:[1,0]
	v_pk_mul_f32 v[214:215], v[60:61], v[216:217] op_sel_hi:[1,0]
	v_exp_f32_e32 v212, v212
	v_exp_f32_e32 v213, v213
	v_exp_f32_e32 v214, v214
	v_exp_f32_e32 v215, v215
	v_pk_mul_f32 v[150:151], v[58:59], v[26:27]
	v_pk_fma_f32 v[212:213], v[212:213], v[218:219], v[218:219] op_sel_hi:[1,0,0]
	v_pk_mul_f32 v[152:153], v[60:61], v[28:29]
	v_pk_fma_f32 v[214:215], v[214:215], v[218:219], v[218:219] op_sel_hi:[1,0,0]
	v_rcp_f32_e32 v212, v212
	v_rcp_f32_e32 v213, v213
	v_rcp_f32_e32 v214, v214
	v_rcp_f32_e32 v215, v215
	v_pk_mul_f32 v[150:151], v[150:151], v[212:213]
	v_pk_mul_f32 v[152:153], v[152:153], v[214:215]
	s_mov_b64 s[52:53], -1
	v_cvt_pk_bf16_f32 v130, v132, v133
	v_cvt_pk_bf16_f32 v131, v148, v149
	v_cvt_pk_bf16_f32 v132, v150, v151
	v_cvt_pk_bf16_f32 v133, v152, v153
	s_mov_b32 s98, 0x5000
	s_mov_b32 s99, 0x0
	v_lshl_add_u64 v[172:173], v[170:171], 0, s[98:99]
	s_cbranch_vccnz .Lcr1_2144
	s_mov_b64 s[52:53], 0
	global_store_dwordx4 v[172:173], v[130:133], off offset:-4096

.Lcr1_2146:
	s_waitcnt lgkmcnt(2)
	s_nop 0
	s_nop 0
	v_mov_b32_e32 v130, v251
	s_and_b64 vcc, exec, s[10:11]
	s_mov_b64 s[52:53], -1
	v_mul_f32_e32 v216, s30, v130
	v_mul_f32_e32 v218, v130, v130
	s_nop 0
	v_rcp_f32_e32 v218, v218
	v_pk_mul_f32 v[212:213], v[54:55], v[216:217] op_sel_hi:[1,0]
	v_pk_mul_f32 v[214:215], v[56:57], v[216:217] op_sel_hi:[1,0]
	v_exp_f32_e32 v212, v212
	v_exp_f32_e32 v213, v213
	v_exp_f32_e32 v214, v214
	v_exp_f32_e32 v215, v215
	v_pk_mul_f32 v[132:133], v[54:55], v[22:23]
	v_pk_fma_f32 v[212:213], v[212:213], v[218:219], v[218:219] op_sel_hi:[1,0,0]
	v_pk_mul_f32 v[144:145], v[56:57], v[24:25]
	v_pk_fma_f32 v[214:215], v[214:215], v[218:219], v[218:219] op_sel_hi:[1,0,0]
	v_rcp_f32_e32 v212, v212
	v_rcp_f32_e32 v213, v213
	v_rcp_f32_e32 v214, v214
	v_rcp_f32_e32 v215, v215
	v_pk_mul_f32 v[132:133], v[132:133], v[212:213]
	v_pk_mul_f32 v[144:145], v[144:145], v[214:215]
	v_pk_mul_f32 v[212:213], v[50:51], v[216:217] op_sel_hi:[1,0]
	v_pk_mul_f32 v[214:215], v[52:53], v[216:217] op_sel_hi:[1,0]
	v_exp_f32_e32 v212, v212
	v_exp_f32_e32 v213, v213
	v_exp_f32_e32 v214, v214
	v_exp_f32_e32 v215, v215
	v_pk_mul_f32 v[146:147], v[50:51], v[18:19]
	v_pk_fma_f32 v[212:213], v[212:213], v[218:219], v[218:219] op_sel_hi:[1,0,0]
	v_pk_mul_f32 v[148:149], v[52:53], v[20:21]
	v_pk_fma_f32 v[214:215], v[214:215], v[218:219], v[218:219] op_sel_hi:[1,0,0]
	v_rcp_f32_e32 v212, v212
	v_rcp_f32_e32 v213, v213
	v_rcp_f32_e32 v214, v214
	v_rcp_f32_e32 v215, v215
	v_pk_mul_f32 v[146:147], v[146:147], v[212:213]
	v_pk_mul_f32 v[148:149], v[148:149], v[214:215]
	v_cvt_pk_bf16_f32 v130, v132, v133
	v_cvt_pk_bf16_f32 v131, v144, v145
	v_cvt_pk_bf16_f32 v132, v146, v147
	v_cvt_pk_bf16_f32 v133, v148, v149
	s_cbranch_vccnz .Lcr1_2148
	s_mov_b64 s[52:53], 0
	global_store_dwordx4 v[172:173], v[130:133], off offset:-2048

.Lcr1_2150:
	s_waitcnt lgkmcnt(1)
	s_nop 0
	s_nop 0
	v_mov_b32_e32 v130, v252
	s_and_b64 vcc, exec, s[10:11]
	s_mov_b64 s[52:53], -1
	v_mul_f32_e32 v216, s30, v130
	v_mul_f32_e32 v218, v130, v130
	s_nop 0
	v_rcp_f32_e32 v218, v218
	v_pk_mul_f32 v[212:213], v[46:47], v[216:217] op_sel_hi:[1,0]
	v_pk_mul_f32 v[214:215], v[48:49], v[216:217] op_sel_hi:[1,0]
	v_exp_f32_e32 v212, v212
	v_exp_f32_e32 v213, v213
	v_exp_f32_e32 v214, v214
	v_exp_f32_e32 v215, v215
	v_pk_mul_f32 v[132:133], v[46:47], v[14:15]
	v_pk_fma_f32 v[212:213], v[212:213], v[218:219], v[218:219] op_sel_hi:[1,0,0]
	v_pk_mul_f32 v[142:143], v[48:49], v[16:17]
	v_pk_fma_f32 v[214:215], v[214:215], v[218:219], v[218:219] op_sel_hi:[1,0,0]
	v_rcp_f32_e32 v212, v212
	v_rcp_f32_e32 v213, v213
	v_rcp_f32_e32 v214, v214
	v_rcp_f32_e32 v215, v215
	v_pk_mul_f32 v[132:133], v[132:133], v[212:213]
	v_pk_mul_f32 v[142:143], v[142:143], v[214:215]
	v_pk_mul_f32 v[212:213], v[42:43], v[216:217] op_sel_hi:[1,0]
	v_pk_mul_f32 v[214:215], v[44:45], v[216:217] op_sel_hi:[1,0]
	v_exp_f32_e32 v212, v212
	v_exp_f32_e32 v213, v213
	v_exp_f32_e32 v214, v214
	v_exp_f32_e32 v215, v215
	v_pk_mul_f32 v[144:145], v[42:43], v[10:11]
	v_pk_fma_f32 v[212:213], v[212:213], v[218:219], v[218:219] op_sel_hi:[1,0,0]
	v_pk_mul_f32 v[146:147], v[44:45], v[12:13]
	v_pk_fma_f32 v[214:215], v[214:215], v[218:219], v[218:219] op_sel_hi:[1,0,0]
	v_rcp_f32_e32 v212, v212
	v_rcp_f32_e32 v213, v213
	v_rcp_f32_e32 v214, v214
	v_rcp_f32_e32 v215, v215
	v_pk_mul_f32 v[144:145], v[144:145], v[212:213]
	v_pk_mul_f32 v[146:147], v[146:147], v[214:215]
	v_cvt_pk_bf16_f32 v130, v132, v133
	v_cvt_pk_bf16_f32 v131, v142, v143
	v_cvt_pk_bf16_f32 v132, v144, v145
	v_cvt_pk_bf16_f32 v133, v146, v147
	s_cbranch_vccnz .Lcr1_2152
	s_mov_b64 s[52:53], 0
	global_store_dwordx4 v[172:173], v[130:133], off

.Lcr1_2154:
	s_waitcnt lgkmcnt(0)
	s_nop 0
	s_nop 0
	v_mov_b32_e32 v130, v253
	s_and_b64 vcc, exec, s[10:11]
	s_mov_b64 s[10:11], -1
	v_mul_f32_e32 v216, s30, v130
	v_mul_f32_e32 v218, v130, v130
	s_nop 0
	v_rcp_f32_e32 v218, v218
	v_pk_mul_f32 v[212:213], v[38:39], v[216:217] op_sel_hi:[1,0]
	v_pk_mul_f32 v[214:215], v[40:41], v[216:217] op_sel_hi:[1,0]
	v_exp_f32_e32 v212, v212
	v_exp_f32_e32 v213, v213
	v_exp_f32_e32 v214, v214
	v_exp_f32_e32 v215, v215
	v_pk_mul_f32 v[132:133], v[38:39], v[6:7]
	v_pk_fma_f32 v[212:213], v[212:213], v[218:219], v[218:219] op_sel_hi:[1,0,0]
	v_pk_mul_f32 v[140:141], v[40:41], v[8:9]
	v_pk_fma_f32 v[214:215], v[214:215], v[218:219], v[218:219] op_sel_hi:[1,0,0]
	v_rcp_f32_e32 v212, v212
	v_rcp_f32_e32 v213, v213
	v_rcp_f32_e32 v214, v214
	v_rcp_f32_e32 v215, v215
	v_pk_mul_f32 v[132:133], v[132:133], v[212:213]
	v_pk_mul_f32 v[140:141], v[140:141], v[214:215]
	v_pk_mul_f32 v[212:213], v[34:35], v[216:217] op_sel_hi:[1,0]
	v_pk_mul_f32 v[214:215], v[36:37], v[216:217] op_sel_hi:[1,0]
	v_exp_f32_e32 v212, v212
	v_exp_f32_e32 v213, v213
	v_exp_f32_e32 v214, v214
	v_exp_f32_e32 v215, v215
	v_pk_mul_f32 v[142:143], v[34:35], v[2:3]
	v_pk_fma_f32 v[212:213], v[212:213], v[218:219], v[218:219] op_sel_hi:[1,0,0]
	v_pk_mul_f32 v[144:145], v[36:37], v[4:5]
	v_pk_fma_f32 v[214:215], v[214:215], v[218:219], v[218:219] op_sel_hi:[1,0,0]
	v_rcp_f32_e32 v212, v212
	v_rcp_f32_e32 v213, v213
	v_rcp_f32_e32 v214, v214
	v_rcp_f32_e32 v215, v215
	v_pk_mul_f32 v[142:143], v[142:143], v[212:213]
	v_pk_mul_f32 v[144:145], v[144:145], v[214:215]
	v_cvt_pk_bf16_f32 v130, v132, v133
	v_cvt_pk_bf16_f32 v131, v140, v141
	v_cvt_pk_bf16_f32 v132, v142, v143
	v_cvt_pk_bf16_f32 v133, v144, v145
	s_cbranch_vccnz .Lcr1_2156
	s_mov_b64 s[10:11], 0
	global_store_dwordx4 v[172:173], v[130:133], off offset:2048
